# attention epilogue: z loads hoisted under last PV, one wait, 16 independent pack+store groups (was a 16-step load-wait-store ladder)
# speedup vs baseline: 1.0061x; 1.0061x over previous
; #define SBAR() __builtin_amdgcn_sched_barrier(0)
; __device__ __forceinline__ void qkt3(f32x16& p0, f32x16& p1, const bf16* Ks, const bf16x8* qr, int r32, int hi, const f32x16& cinit) {
;   { int cb = (hi * 8) * 2;
;     bf16x8 b0 = *reinterpret_cast<const bf16x8*>((const char*)Ks + KSWZ(r32, cb));
;     bf16x8 b1 = *reinterpret_cast<const bf16x8*>((const char*)Ks + KSWZ(32 + r32, cb));
;     p0 = __builtin_amdgcn_mfma_f32_32x32x16_bf16(b0, qr[0], cinit, 0, 0, 0);
;     p1 = __builtin_amdgcn_mfma_f32_32x32x16_bf16(b1, qr[0], cinit, 0, 0, 0); }
;   for (int d0 = 1; d0 < 8; ++d0) { int cb = (d0 * 16 + hi * 8) * 2;
;     bf16x8 b0 = *reinterpret_cast<const bf16x8*>((const char*)Ks + KSWZ(r32, cb));
;     bf16x8 b1 = *reinterpret_cast<const bf16x8*>((const char*)Ks + KSWZ(32 + r32, cb));
;     p0 = __builtin_amdgcn_mfma_f32_32x32x16_bf16(b0, qr[d0], p0, 0, 0, 0);
;     p1 = __builtin_amdgcn_mfma_f32_32x32x16_bf16(b1, qr[d0], p1, 0, 0, 0); }
; }
; __device__ __forceinline__ int v_st(int k, int c) { const int kk = (k & ~0xC) | ((k & 4) << 1) | ((k & 8) >> 1); return ((kk >> 3) * 4 + (c >> 5)) * 512 + ((kk & 7) * 32 + (c & 31)) * 2; }
; __device__ __forceinline__ int v_rd_base(int lane) { return ((lane & 3) << 3) | (((lane >> 2) & 3) << 6) | (((lane >> 4) & 1) << 5) | (((lane >> 5) & 1) << 8); }
; template <int OFF> __device__ __forceinline__ s16x4 tr_read(int vb) {
;   s16x4 r; asm volatile("ds_read_b64_tr_b16 %0, %1 offset:%2" : "=&v"(r) : "v"(vb), "i"(OFF) : "memory"); return r;
; }
; template <int D0> __device__ __forceinline__ void pv_one(f32x16& od, int vb, bf16x8 pa0, bf16x8 pa1, bf16x8 pa2, bf16x8 pa3) {
;   const s16x4 l0 = tr_read<v_rd_off(D0, 0, 0)>(vb), h0 = tr_read<v_rd_off(D0, 0, 1)>(vb), l1 = tr_read<v_rd_off(D0, 1, 0)>(vb), h1 = tr_read<v_rd_off(D0, 1, 1)>(vb);
;   const s16x4 l2 = tr_read<v_rd_off(D0, 2, 0)>(vb), h2 = tr_read<v_rd_off(D0, 2, 1)>(vb), l3 = tr_read<v_rd_off(D0, 3, 0)>(vb), h3 = tr_read<v_rd_off(D0, 3, 1)>(vb);
;   asm volatile("s_waitcnt lgkmcnt(0)" ::: "memory"); SBAR();
;     ...
;   od = __builtin_amdgcn_mfma_f32_32x32x16_bf16(pa0, PK(l0, h0), od, 0, 0, 0);
;   od = __builtin_amdgcn_mfma_f32_32x32x16_bf16(pa1, PK(l1, h1), od, 0, 0, 0);
;   od = __builtin_amdgcn_mfma_f32_32x32x16_bf16(pa2, PK(l2, h2), od, 0, 0, 0);
;   od = __builtin_amdgcn_mfma_f32_32x32x16_bf16(pa3, PK(l3, h3), od, 0, 0, 0);
;     ...
; }
.LBB0_117:
	s_lshl_b32 s49, s48, 14
	s_add_i32 s14, s90, s49
	v_lshl_add_u64 v[224:225], s[40:41], 0, v[154:155]
	s_add_i32 m0, s14, 0xc000
	v_lshl_add_u64 v[80:81], v[224:225], 0, s[70:71]
	v_lshl_add_u64 v[226:227], s[40:41], 0, v[152:153]
	global_load_lds_dwordx4 v[80:81], off
	v_lshl_add_u64 v[80:81], v[226:227], 0, s[70:71]
	s_add_i32 m0, s14, 0xc400
	v_lshl_add_u64 v[228:229], s[40:41], 0, v[150:151]
	global_load_lds_dwordx4 v[80:81], off
	v_lshl_add_u64 v[80:81], v[228:229], 0, s[58:59]
	s_mov_b32 m0, s14
	v_lshl_add_u64 v[230:231], s[40:41], 0, v[148:149]
	global_load_lds_dwordx4 v[80:81], off
	v_lshl_add_u64 v[80:81], v[230:231], 0, s[58:59]
	s_add_i32 m0, s14, 0x400
	s_mov_b32 s53, s46
	global_load_lds_dwordx4 v[80:81], off
	s_mov_b32 s46, s54
	s_lshl_b32 s15, s53, 14
	s_add_i32 s14, s15, 0
	v_add_u32_e32 v84, s14, v157
	ds_read_b128 v[80:83], v84 offset:49152
	ds_read_b128 v[246:249], v84 offset:57344
	v_add_u32_e32 v162, s14, v177
	v_cvt_pk_bf16_f32 v185, v202, v204
	v_cvt_pk_bf16_f32 v191, v180, v182
	s_waitcnt lgkmcnt(0)
	v_mfma_f32_32x32x16_bf16 v[96:111], v[80:83], v[140:143], v[64:79]
	v_cvt_pk_bf16_f32 v181, v212, v214
	v_cvt_pk_bf16_f32 v187, v220, v222
	v_cvt_pk_bf16_f32 v189, v158, v166
	v_mfma_f32_32x32x16_bf16 v[80:95], v[246:249], v[140:143], v[64:79]
	ds_read_b128 v[246:249], v162 offset:49152
	ds_read_b128 v[238:241], v162 offset:57344
	v_add_u32_e32 v162, s14, v175
	s_waitcnt lgkmcnt(0)
	v_mfma_f32_32x32x16_bf16 v[96:111], v[246:249], v[136:139], v[96:111]
	v_mfma_f32_32x32x16_bf16 v[80:95], v[238:241], v[136:139], v[80:95]
	ds_read_b128 v[238:241], v162 offset:49152
	ds_read_b128 v[246:249], v162 offset:57344
	v_add_u32_e32 v162, s14, v173
	s_waitcnt lgkmcnt(0)
	v_mfma_f32_32x32x16_bf16 v[96:111], v[238:241], v[132:135], v[96:111]
	v_mfma_f32_32x32x16_bf16 v[80:95], v[246:249], v[132:135], v[80:95]
	ds_read_b128 v[238:241], v162 offset:49152
	ds_read_b128 v[246:249], v162 offset:57344
	v_add_u32_e32 v162, s14, v171
	s_waitcnt lgkmcnt(0)
	v_mfma_f32_32x32x16_bf16 v[96:111], v[238:241], v[128:131], v[96:111]
	v_mfma_f32_32x32x16_bf16 v[80:95], v[246:249], v[128:131], v[80:95]
	ds_read_b128 v[238:241], v162 offset:49152
	ds_read_b128 v[246:249], v162 offset:57344
	v_add_u32_e32 v162, s14, v169
	s_waitcnt lgkmcnt(0)
	v_mfma_f32_32x32x16_bf16 v[96:111], v[238:241], v[124:127], v[96:111]
	v_mfma_f32_32x32x16_bf16 v[80:95], v[246:249], v[124:127], v[80:95]
	ds_read_b128 v[238:241], v162 offset:49152
	ds_read_b128 v[246:249], v162 offset:57344
	v_add_u32_e32 v162, s14, v167
	s_waitcnt lgkmcnt(0)
	v_mfma_f32_32x32x16_bf16 v[96:111], v[238:241], v[120:123], v[96:111]
	v_mfma_f32_32x32x16_bf16 v[80:95], v[246:249], v[120:123], v[80:95]
	ds_read_b128 v[238:241], v162 offset:49152
	ds_read_b128 v[246:249], v162 offset:57344
	v_add_u32_e32 v162, s14, v159
	s_lshl_b32 s14, s54, 14
	s_waitcnt lgkmcnt(0)
	v_mfma_f32_32x32x16_bf16 v[96:111], v[238:241], v[116:119], v[96:111]
	v_mfma_f32_32x32x16_bf16 v[80:95], v[246:249], v[116:119], v[80:95]
	ds_read_b128 v[238:241], v162 offset:49152
	ds_read_b128 v[246:249], v162 offset:57344
	v_add_f32_e32 v162, 0, v179
	v_add_f32_e32 v162, v170, v162
	v_add_f32_e32 v162, v172, v162
	v_add_f32_e32 v162, v174, v162
	v_add_f32_e32 v162, v184, v162
	v_add_f32_e32 v162, v186, v162
	v_add_f32_e32 v162, v188, v162
	v_add_f32_e32 v162, v190, v162
	v_add_f32_e32 v162, v206, v162
	v_add_f32_e32 v162, v200, v162
	v_add_f32_e32 v162, v202, v162
	v_add_f32_e32 v162, v204, v162
	v_add_f32_e32 v162, v216, v162
	v_add_f32_e32 v162, v218, v162
	v_add_f32_e32 v162, v220, v162
	v_add_f32_e32 v162, v222, v162
	v_add_f32_e32 v162, v168, v162
	v_add_f32_e32 v162, v156, v162
	v_add_f32_e32 v162, v158, v162
	v_add_f32_e32 v162, v166, v162
	v_add_f32_e32 v162, v176, v162
	v_add_f32_e32 v162, v178, v162
	v_add_f32_e32 v162, v180, v162
	v_add_f32_e32 v162, v182, v162
	v_add_f32_e32 v162, v198, v162
	v_add_f32_e32 v162, v196, v162
	s_waitcnt lgkmcnt(0)
	v_mfma_f32_32x32x16_bf16 v[96:111], v[238:241], v[112:115], v[96:111]
	v_add_f32_e32 v162, v192, v162
	v_cvt_pk_bf16_f32 v238, v179, v170
	v_cvt_pk_bf16_f32 v179, v192, v194
	v_add_f32_e32 v162, v194, v162
	v_cvt_pk_bf16_f32 v241, v188, v190
	v_cvt_pk_bf16_f32 v190, v176, v178
	v_cvt_pk_bf16_f32 v178, v198, v196
	v_mfma_f32_32x32x16_bf16 v[80:95], v[246:249], v[112:115], v[80:95]
	v_add_u32_e32 v246, s14, v147
	ds_read_b64_tr_b16 v[192:193], v246 offset:0
	ds_read_b64_tr_b16 v[194:195], v246 offset:0x100
	ds_read_b64_tr_b16 v[196:197], v246 offset:0x1000
	ds_read_b64_tr_b16 v[198:199], v246 offset:0x1100
	v_cvt_pk_bf16_f32 v240, v184, v186
	v_cvt_pk_bf16_f32 v184, v206, v200
	ds_read_b64_tr_b16 v[200:201], v246 offset:0x2000
	ds_read_b64_tr_b16 v[202:203], v246 offset:0x2100
	ds_read_b64_tr_b16 v[204:205], v246 offset:0x3000
	ds_read_b64_tr_b16 v[206:207], v246 offset:0x3100
	v_add_f32_e32 v162, v208, v162
	v_cvt_pk_bf16_f32 v180, v208, v210
	ds_read_b64_tr_b16 v[208:209], v246 offset:0x200
	v_add_f32_e32 v162, v210, v162
	ds_read_b64_tr_b16 v[210:211], v246 offset:0x300
	v_add_f32_e32 v162, v212, v162
	ds_read_b64_tr_b16 v[212:213], v246 offset:0x1200
	v_add_f32_e32 v162, v214, v162
	ds_read_b64_tr_b16 v[214:215], v246 offset:0x1300
	v_cvt_pk_bf16_f32 v186, v216, v218
	ds_read_b64_tr_b16 v[216:217], v246 offset:0x2200
	ds_read_b64_tr_b16 v[218:219], v246 offset:0x2300
	ds_read_b64_tr_b16 v[220:221], v246 offset:0x3200
	ds_read_b64_tr_b16 v[222:223], v246 offset:0x3300
	s_waitcnt lgkmcnt(8)
; #define SBAR() __builtin_amdgcn_sched_barrier(0)
; #define PV_RD2(D0, X) const s16x4 X##l0 = tr_read<v_rd_off2(D0, 0, 0)>(vb), X##h0 = tr_read<v_rd_off2(D0, 0, 1)>(vb), X##l1 = tr_read<v_rd_off2(D0, 1, 0)>(vb), X##h1 = tr_read<v_rd_off2(D0, 1, 1)>(vb), \
;                               X##l2 = tr_read<v_rd_off2(D0, 2, 0)>(vb), X##h2 = tr_read<v_rd_off2(D0, 2, 1)>(vb), X##l3 = tr_read<v_rd_off2(D0, 3, 0)>(vb), X##h3 = tr_read<v_rd_off2(D0, 3, 1)>(vb)
; #define EXP4(P, B) do { P[(B) + 0] = __builtin_amdgcn_exp2f(P[(B) + 0]); P[(B) + 1] = __builtin_amdgcn_exp2f(P[(B) + 1]); P[(B) + 2] = __builtin_amdgcn_exp2f(P[(B) + 2]); P[(B) + 3] = __builtin_amdgcn_exp2f(P[(B) + 3]); } while (0)
; #define DWAIT() asm volatile("s_waitcnt vmcnt(0)" ::: "memory")
; #define ROT() do { const int t_ = sP; sP = sC; sC = sN; sN = t_; } while (0)
; __device__ __forceinline__ void pv_d03(f32x16* o, int vb, bf16x8 pa0, bf16x8 pa1, bf16x8 pa2, bf16x8 pa3, f32x16& pn, f32x16& pm) {
;   PV_RD2(0, a);
;   PV_RD2(1, b); asm volatile("s_waitcnt lgkmcnt(8)" ::: "memory"); SBAR(); PV_MM2(o[0], a); EXP4(pn, 0); EXP4(pm, 0); SBAR();
;   PV_RD2(2, c); asm volatile("s_waitcnt lgkmcnt(8)" ::: "memory"); SBAR(); PV_MM2(o[1], b); EXP4(pn, 4); EXP4(pm, 4); SBAR();
;   PV_RD2(3, d); asm volatile("s_waitcnt lgkmcnt(8)" ::: "memory"); SBAR(); PV_MM2(o[2], c); EXP4(pn, 8); EXP4(pm, 8); SBAR();
;   asm volatile("s_waitcnt lgkmcnt(0)" ::: "memory"); SBAR(); PV_MM2(o[3], d); EXP4(pn, 12); EXP4(pm, 12);
; }
; __device__ __forceinline__ void attn_dense_body(const bf16* Qb, const bf16* __restrict__ Kh, const bf16* __restrict__ Vh, const bf16* __restrict__ Zb, ...
;     ...
;     DWAIT(); __syncthreads(); ROT();
;     SDMA(sN, (j + 2) * KVBLK);
;     SBAR(); qkt3(pA0, pA1, KSLOT(sC), qr, r32, hi, cinit);
;     finishSM4<16>(pB0, pB1, l_reg, pa0, pa1, pa2, pa3);
;     pv_d03(o, vb0 + sP * (int)SHM_V, pa0, pa1, pa2, pa3, pA0, pA1);
	v_add_f32_e32 v146, v146, v162
	v_cvt_pk_bf16_f32 v188, v168, v156
	v_cvt_pk_bf16_f32 v239, v172, v174
	s_nop 1
	v_mfma_f32_32x32x16_bf16 v[48:63], v[192:195], v[238:241], v[48:63]
	v_exp_f32_e32 v156, v96
	v_exp_f32_e32 v158, v97
	v_exp_f32_e32 v166, v82
	v_exp_f32_e32 v168, v83
	v_exp_f32_e32 v162, v98
	v_exp_f32_e32 v163, v99
	v_exp_f32_e32 v164, v80
	v_mfma_f32_32x32x16_bf16 v[48:63], v[196:199], v[184:187], v[48:63]
	v_exp_f32_e32 v165, v81
	v_mfma_f32_32x32x16_bf16 v[48:63], v[200:203], v[188:191], v[48:63]
	v_mfma_f32_32x32x16_bf16 v[48:63], v[204:207], v[178:181], v[48:63]
	ds_read_b64_tr_b16 v[80:81], v246 offset:0x400
	ds_read_b64_tr_b16 v[82:83], v246 offset:0x500
	ds_read_b64_tr_b16 v[96:97], v246 offset:0x1400
	ds_read_b64_tr_b16 v[98:99], v246 offset:0x1500
	ds_read_b64_tr_b16 v[192:193], v246 offset:0x2400
	ds_read_b64_tr_b16 v[194:195], v246 offset:0x2500
	ds_read_b64_tr_b16 v[196:197], v246 offset:0x3400
	ds_read_b64_tr_b16 v[198:199], v246 offset:0x3500
	s_waitcnt lgkmcnt(8)
	v_mfma_f32_32x32x16_bf16 v[32:47], v[208:211], v[238:241], v[32:47]
	v_exp_f32_e32 v170, v100
	v_exp_f32_e32 v172, v101
	v_exp_f32_e32 v174, v102
	v_exp_f32_e32 v176, v103
	v_mfma_f32_32x32x16_bf16 v[32:47], v[212:215], v[184:187], v[32:47]
	v_mfma_f32_32x32x16_bf16 v[32:47], v[216:219], v[188:191], v[32:47]
	v_exp_f32_e32 v216, v84
	v_exp_f32_e32 v218, v86
	v_exp_f32_e32 v217, v85
	v_exp_f32_e32 v219, v87
	v_mfma_f32_32x32x16_bf16 v[32:47], v[220:223], v[178:181], v[32:47]
	ds_read_b64_tr_b16 v[84:85], v246 offset:0x600
	ds_read_b64_tr_b16 v[86:87], v246 offset:0x700
	ds_read_b64_tr_b16 v[100:101], v246 offset:0x1600
	ds_read_b64_tr_b16 v[102:103], v246 offset:0x1700
	ds_read_b64_tr_b16 v[200:201], v246 offset:0x2600
	ds_read_b64_tr_b16 v[202:203], v246 offset:0x2700
	ds_read_b64_tr_b16 v[204:205], v246 offset:0x3600
	ds_read_b64_tr_b16 v[206:207], v246 offset:0x3700
	s_waitcnt lgkmcnt(8)
	v_mfma_f32_32x32x16_bf16 v[16:31], v[80:83], v[238:241], v[16:31]
	v_exp_f32_e32 v220, v88
	v_exp_f32_e32 v222, v90
	v_exp_f32_e32 v221, v89
	v_exp_f32_e32 v223, v91
	v_mfma_f32_32x32x16_bf16 v[16:31], v[96:99], v[184:187], v[16:31]
	v_mfma_f32_32x32x16_bf16 v[16:31], v[192:195], v[188:191], v[16:31]
	v_exp_f32_e32 v192, v104
	v_exp_f32_e32 v194, v106
	v_exp_f32_e32 v193, v105
	v_exp_f32_e32 v195, v107
	v_mfma_f32_32x32x16_bf16 v[16:31], v[196:199], v[178:181], v[16:31]
	s_waitcnt lgkmcnt(0)
	s_add_i32 s16, s90, s14
	s_add_i32 m0, s16, 0xc000
	v_lshl_add_u64 v[80:81], v[224:225], 0, s[30:31]
	s_waitcnt vmcnt(0)
	s_waitcnt vmcnt(0)
	s_barrier
	global_load_lds_dwordx4 v[80:81], off
	v_lshl_add_u64 v[80:81], v[226:227], 0, s[30:31]
	s_add_i32 m0, s16, 0xc400
	v_mfma_f32_32x32x16_bf16 v[0:15], v[84:87], v[238:241], v[0:15]
	global_load_lds_dwordx4 v[80:81], off
	v_lshl_add_u64 v[80:81], v[228:229], 0, s[26:27]
	s_mov_b32 m0, s16
	v_exp_f32_e32 v196, v94
	global_load_lds_dwordx4 v[80:81], off
	v_lshl_add_u64 v[80:81], v[230:231], 0, s[26:27]
	s_add_i32 m0, s16, 0x400
	v_mfma_f32_32x32x16_bf16 v[0:15], v[100:103], v[184:187], v[0:15]
	global_load_lds_dwordx4 v[80:81], off
	v_exp_f32_e32 v186, v108
	v_exp_f32_e32 v187, v109
	v_exp_f32_e32 v197, v95
	v_mfma_f32_32x32x16_bf16 v[0:15], v[200:203], v[188:191], v[0:15]
	v_exp_f32_e32 v188, v110
	v_exp_f32_e32 v190, v92
	v_exp_f32_e32 v189, v111
	v_exp_f32_e32 v191, v93
	v_mfma_f32_32x32x16_bf16 v[0:15], v[204:207], v[178:181], v[0:15]
	s_add_i32 s16, s49, 0
	v_add_u32_e32 v84, s16, v157
	ds_read_b128 v[80:83], v84 offset:49152
	ds_read_b128 v[178:181], v84 offset:57344
	v_add_u32_e32 v182, s16, v177
	v_add_u32_e32 v206, s15, v147
	v_cvt_pk_bf16_f32 v214, v186, v187
	s_waitcnt lgkmcnt(0)
	v_mfma_f32_32x32x16_bf16 v[96:111], v[80:83], v[140:143], v[64:79]
	v_cvt_pk_bf16_f32 v215, v188, v189
	v_cvt_pk_bf16_f32 v230, v190, v191
	v_cvt_pk_bf16_f32 v212, v192, v193
	v_cvt_pk_bf16_f32 v213, v194, v195
	v_cvt_pk_bf16_f32 v231, v196, v197
	v_cvt_pk_bf16_f32 v226, v216, v217
	v_cvt_pk_bf16_f32 v227, v218, v219
	v_mfma_f32_32x32x16_bf16 v[80:95], v[178:181], v[140:143], v[64:79]
	ds_read_b128 v[178:181], v182 offset:49152
	ds_read_b128 v[182:185], v182 offset:57344
	v_cvt_pk_bf16_f32 v208, v156, v158
	v_cvt_pk_bf16_f32 v210, v170, v172
	v_cvt_pk_bf16_f32 v209, v162, v163
	v_cvt_pk_bf16_f32 v211, v174, v176
	v_cvt_pk_bf16_f32 v224, v164, v165
	v_cvt_pk_bf16_f32 v225, v166, v168
	s_waitcnt lgkmcnt(0)
	v_mfma_f32_32x32x16_bf16 v[96:111], v[178:181], v[136:139], v[96:111]
	v_cvt_pk_bf16_f32 v228, v220, v221
	v_cvt_pk_bf16_f32 v229, v222, v223
	v_mfma_f32_32x32x16_bf16 v[80:95], v[182:185], v[136:139], v[80:95]
	v_add_u32_e32 v182, s16, v175
	ds_read_b128 v[178:181], v182 offset:49152
	ds_read_b128 v[182:185], v182 offset:57344
	s_waitcnt lgkmcnt(0)
	v_mfma_f32_32x32x16_bf16 v[96:111], v[178:181], v[132:135], v[96:111]
	v_mfma_f32_32x32x16_bf16 v[80:95], v[182:185], v[132:135], v[80:95]
	v_add_u32_e32 v182, s16, v173
	ds_read_b128 v[178:181], v182 offset:49152
	ds_read_b128 v[182:185], v182 offset:57344
	s_waitcnt lgkmcnt(0)
	v_mfma_f32_32x32x16_bf16 v[96:111], v[178:181], v[128:131], v[96:111]
	v_mfma_f32_32x32x16_bf16 v[80:95], v[182:185], v[128:131], v[80:95]
	v_add_u32_e32 v182, s16, v171
	ds_read_b128 v[178:181], v182 offset:49152
	ds_read_b128 v[182:185], v182 offset:57344
	s_waitcnt lgkmcnt(0)
	v_mfma_f32_32x32x16_bf16 v[96:111], v[178:181], v[124:127], v[96:111]
	v_mfma_f32_32x32x16_bf16 v[80:95], v[182:185], v[124:127], v[80:95]
	v_add_u32_e32 v182, s16, v169
	ds_read_b128 v[178:181], v182 offset:49152
	ds_read_b128 v[182:185], v182 offset:57344
	s_waitcnt lgkmcnt(0)
; #define SBAR() __builtin_amdgcn_sched_barrier(0)
; #define PV_RD2(D0, X) const s16x4 X##l0 = tr_read<v_rd_off2(D0, 0, 0)>(vb), X##h0 = tr_read<v_rd_off2(D0, 0, 1)>(vb), X##l1 = tr_read<v_rd_off2(D0, 1, 0)>(vb), X##h1 = tr_read<v_rd_off2(D0, 1, 1)>(vb), \
;                               X##l2 = tr_read<v_rd_off2(D0, 2, 0)>(vb), X##h2 = tr_read<v_rd_off2(D0, 2, 1)>(vb), X##l3 = tr_read<v_rd_off2(D0, 3, 0)>(vb), X##h3 = tr_read<v_rd_off2(D0, 3, 1)>(vb)
; #define EXP4(P, B) do { P[(B) + 0] = __builtin_amdgcn_exp2f(P[(B) + 0]); P[(B) + 1] = __builtin_amdgcn_exp2f(P[(B) + 1]); P[(B) + 2] = __builtin_amdgcn_exp2f(P[(B) + 2]); P[(B) + 3] = __builtin_amdgcn_exp2f(P[(B) + 3]); } while (0)
; #define DWAIT() asm volatile("s_waitcnt vmcnt(0)" ::: "memory")
; #define ROT() do { const int t_ = sP; sP = sC; sC = sN; sN = t_; } while (0)
; __device__ __forceinline__ void pv_d03(f32x16* o, int vb, bf16x8 pa0, bf16x8 pa1, bf16x8 pa2, bf16x8 pa3, f32x16& pn, f32x16& pm) {
;   PV_RD2(0, a);
;   PV_RD2(1, b); asm volatile("s_waitcnt lgkmcnt(8)" ::: "memory"); SBAR(); PV_MM2(o[0], a); EXP4(pn, 0); EXP4(pm, 0); SBAR();
;   PV_RD2(2, c); asm volatile("s_waitcnt lgkmcnt(8)" ::: "memory"); SBAR(); PV_MM2(o[1], b); EXP4(pn, 4); EXP4(pm, 4); SBAR();
;   PV_RD2(3, d); asm volatile("s_waitcnt lgkmcnt(8)" ::: "memory"); SBAR(); PV_MM2(o[2], c); EXP4(pn, 8); EXP4(pm, 8); SBAR();
;   asm volatile("s_waitcnt lgkmcnt(0)" ::: "memory"); SBAR(); PV_MM2(o[3], d); EXP4(pn, 12); EXP4(pm, 12);
; }
; __device__ __forceinline__ void attn_dense_body(const bf16* Qb, const bf16* __restrict__ Kh, const bf16* __restrict__ Vh, const bf16* __restrict__ Zb, ...
;     ...
;   for (int j = 1; j + 1 < NT; j += 2) {
;     SDMA(sN, (j + 1) * KVBLK);
;     SBAR(); qkt3(pB0, pB1, KSLOT(sC), qr, r32, hi, cinit);
;     finishSM4<16>(pA0, pA1, l_reg, pa0, pa1, pa2, pa3);
;     pv_d03(o, vb0 + sP * (int)SHM_V, pa0, pa1, pa2, pa3, pB0, pB1);
;     DWAIT(); __syncthreads(); ROT();
;     SDMA(sN, (j + 2) * KVBLK);
;     SBAR(); qkt3(pA0, pA1, KSLOT(sC), qr, r32, hi, cinit);
;     finishSM4<16>(pB0, pB1, l_reg, pa0, pa1, pa2, pa3);
;     pv_d03(o, vb0 + sP * (int)SHM_V, pa0, pa1, pa2, pa3, pA0, pA1);
;     DWAIT(); __syncthreads(); ROT();
;   }
	v_mfma_f32_32x32x16_bf16 v[96:111], v[178:181], v[120:123], v[96:111]
	v_mfma_f32_32x32x16_bf16 v[80:95], v[182:185], v[120:123], v[80:95]
	v_add_u32_e32 v182, s16, v167
	ds_read_b128 v[178:181], v182 offset:49152
	ds_read_b128 v[182:185], v182 offset:57344
	s_waitcnt lgkmcnt(0)
	v_mfma_f32_32x32x16_bf16 v[96:111], v[178:181], v[116:119], v[96:111]
	v_mfma_f32_32x32x16_bf16 v[80:95], v[182:185], v[116:119], v[80:95]
	v_add_u32_e32 v182, s16, v159
	ds_read_b128 v[178:181], v182 offset:49152
	ds_read_b128 v[182:185], v182 offset:57344
	s_waitcnt lgkmcnt(0)
	v_mfma_f32_32x32x16_bf16 v[96:111], v[178:181], v[112:115], v[96:111]
	v_add_f32_e32 v178, 0, v156
	v_add_f32_e32 v178, v158, v178
	v_add_f32_e32 v178, v162, v178
	v_add_f32_e32 v178, v163, v178
	v_add_f32_e32 v178, v170, v178
	v_add_f32_e32 v178, v172, v178
	v_add_f32_e32 v178, v174, v178
	v_add_f32_e32 v178, v176, v178
	v_add_f32_e32 v178, v192, v178
	v_add_f32_e32 v178, v193, v178
	v_add_f32_e32 v178, v194, v178
	v_add_f32_e32 v178, v195, v178
	v_add_f32_e32 v178, v186, v178
	v_add_f32_e32 v178, v187, v178
	v_add_f32_e32 v178, v188, v178
	v_add_f32_e32 v178, v189, v178
	v_add_f32_e32 v178, v164, v178
	v_add_f32_e32 v178, v165, v178
	v_add_f32_e32 v178, v166, v178
	v_add_f32_e32 v178, v168, v178
	v_add_f32_e32 v178, v216, v178
	v_add_f32_e32 v178, v217, v178
	v_add_f32_e32 v178, v218, v178
	v_add_f32_e32 v178, v219, v178
	v_add_f32_e32 v178, v220, v178
	v_add_f32_e32 v178, v221, v178
	v_add_f32_e32 v178, v222, v178
	v_add_f32_e32 v178, v223, v178
	v_add_f32_e32 v178, v190, v178
	v_add_f32_e32 v178, v191, v178
	v_add_f32_e32 v178, v196, v178
	v_add_f32_e32 v178, v197, v178
	v_add_f32_e32 v146, v146, v178
	ds_read_b64_tr_b16 v[178:179], v206 offset:0
	ds_read_b64_tr_b16 v[180:181], v206 offset:0x100
	v_mfma_f32_32x32x16_bf16 v[80:95], v[182:185], v[112:115], v[80:95]
	ds_read_b64_tr_b16 v[182:183], v206 offset:0x1000
	ds_read_b64_tr_b16 v[184:185], v206 offset:0x1100
	ds_read_b64_tr_b16 v[186:187], v206 offset:0x2000
	ds_read_b64_tr_b16 v[188:189], v206 offset:0x2100
	ds_read_b64_tr_b16 v[190:191], v206 offset:0x3000
	ds_read_b64_tr_b16 v[192:193], v206 offset:0x3100
	ds_read_b64_tr_b16 v[194:195], v206 offset:0x200
	ds_read_b64_tr_b16 v[196:197], v206 offset:0x300
	ds_read_b64_tr_b16 v[198:199], v206 offset:0x1200
	ds_read_b64_tr_b16 v[200:201], v206 offset:0x1300
	ds_read_b64_tr_b16 v[202:203], v206 offset:0x2200
	ds_read_b64_tr_b16 v[204:205], v206 offset:0x2300
	ds_read_b64_tr_b16 v[216:217], v206 offset:0x3200
	ds_read_b64_tr_b16 v[218:219], v206 offset:0x3300
	s_waitcnt lgkmcnt(8)
	v_mfma_f32_32x32x16_bf16 v[48:63], v[178:181], v[208:211], v[48:63]
	v_exp_f32_e32 v179, v96
	v_exp_f32_e32 v170, v97
	v_exp_f32_e32 v172, v98
	v_exp_f32_e32 v174, v99
	s_nop 6
	v_exp_f32_e32 v168, v80
	v_exp_f32_e32 v156, v81
	v_exp_f32_e32 v158, v82
	v_mfma_f32_32x32x16_bf16 v[48:63], v[182:185], v[212:215], v[48:63]
	v_exp_f32_e32 v166, v83
	v_mfma_f32_32x32x16_bf16 v[48:63], v[186:189], v[224:227], v[48:63]
	v_mfma_f32_32x32x16_bf16 v[48:63], v[190:193], v[228:231], v[48:63]
	ds_read_b64_tr_b16 v[80:81], v206 offset:0x400
	ds_read_b64_tr_b16 v[82:83], v206 offset:0x500
	ds_read_b64_tr_b16 v[96:97], v206 offset:0x1400
	ds_read_b64_tr_b16 v[98:99], v206 offset:0x1500
	ds_read_b64_tr_b16 v[220:221], v206 offset:0x2400
	ds_read_b64_tr_b16 v[222:223], v206 offset:0x2500
	ds_read_b64_tr_b16 v[238:239], v206 offset:0x3400
	ds_read_b64_tr_b16 v[240:241], v206 offset:0x3500
	s_waitcnt lgkmcnt(8)
	v_mfma_f32_32x32x16_bf16 v[32:47], v[194:197], v[208:211], v[32:47]
	v_exp_f32_e32 v184, v100
	v_exp_f32_e32 v186, v101
	v_exp_f32_e32 v188, v102
	v_exp_f32_e32 v190, v103
	v_exp_f32_e32 v176, v84
	v_exp_f32_e32 v178, v85
	v_exp_f32_e32 v180, v86
	v_mfma_f32_32x32x16_bf16 v[32:47], v[198:201], v[212:215], v[32:47]
	v_exp_f32_e32 v182, v87
	v_mfma_f32_32x32x16_bf16 v[32:47], v[202:205], v[224:227], v[32:47]
	v_mfma_f32_32x32x16_bf16 v[32:47], v[216:219], v[228:231], v[32:47]
	ds_read_b64_tr_b16 v[84:85], v206 offset:0x600
	ds_read_b64_tr_b16 v[86:87], v206 offset:0x700
	ds_read_b64_tr_b16 v[100:101], v206 offset:0x1600
	ds_read_b64_tr_b16 v[102:103], v206 offset:0x1700
	ds_read_b64_tr_b16 v[248:249], v206 offset:0x2600
	ds_read_b64_tr_b16 v[250:251], v206 offset:0x2700
	ds_read_b64_tr_b16 v[162:163], v206 offset:0x3600
	ds_read_b64_tr_b16 v[164:165], v206 offset:0x3700
	s_waitcnt lgkmcnt(8)
	v_mfma_f32_32x32x16_bf16 v[16:31], v[80:83], v[208:211], v[16:31]
	v_exp_f32_e32 v206, v104
	v_exp_f32_e32 v200, v105
	v_exp_f32_e32 v202, v106
	v_exp_f32_e32 v204, v107
	v_exp_f32_e32 v198, v88
	v_exp_f32_e32 v196, v89
	v_exp_f32_e32 v192, v90
	v_mfma_f32_32x32x16_bf16 v[16:31], v[96:99], v[212:215], v[16:31]
	v_exp_f32_e32 v194, v91
	v_mfma_f32_32x32x16_bf16 v[16:31], v[220:223], v[224:227], v[16:31]
	v_mfma_f32_32x32x16_bf16 v[16:31], v[238:241], v[228:231], v[16:31]
	s_waitcnt lgkmcnt(0)
	v_mfma_f32_32x32x16_bf16 v[0:15], v[84:87], v[208:211], v[0:15]
	v_exp_f32_e32 v216, v108
	v_exp_f32_e32 v218, v109
	v_exp_f32_e32 v220, v110
	v_exp_f32_e32 v222, v111
	v_exp_f32_e32 v208, v92
	v_exp_f32_e32 v210, v93
	s_waitcnt vmcnt(0)
	v_mfma_f32_32x32x16_bf16 v[0:15], v[100:103], v[212:215], v[0:15]
	v_exp_f32_e32 v212, v94
	v_exp_f32_e32 v214, v95
	s_add_u32 s40, s40, 0x10000
	s_addc_u32 s41, s41, 0
	s_add_i32 s47, s47, 2
	s_mov_b32 s54, s48
	s_cmp_lt_u32 s47, s52
	v_mfma_f32_32x32x16_bf16 v[0:15], v[248:251], v[224:227], v[0:15]
	s_mov_b32 s48, s53
	s_waitcnt vmcnt(0)
	s_barrier
	v_mfma_f32_32x32x16_bf16 v[0:15], v[162:165], v[228:231], v[0:15]
	s_cbranch_scc1 .LBB0_117
; #define SBAR() __builtin_amdgcn_sched_barrier(0)
; __device__ __forceinline__ void attn_dense_body(const bf16* Qb, const bf16* __restrict__ Kh, const bf16* __restrict__ Vh, const bf16* __restrict__ Zb, ...
;     ...
;   SBAR(); qkt3(pB0, pB1, KSLOT(sC), qr, r32, hi, cinit);
;   finishSM4<16>(pA0, pA1, l_reg, pa0, pa1, pa2, pa3); SBAR();
;   pv_d03(o, vb0 + sP * (int)SHM_V, pa0, pa1, pa2, pa3, pB0, pB1);
	s_add_u32 s40, s36, s44
	s_addc_u32 s41, s50, s45
	s_add_i32 s14, s14, 0
	v_add_u32_e32 v100, s14, v157
	ds_read_b128 v[96:99], v100 offset:49152
	v_add_u32_e32 v104, s14, v159
	v_add_f32_e32 v148, 0, v179
	v_cvt_pk_bf16_f32 v108, v179, v170
	v_cvt_pk_bf16_f32 v109, v172, v174
	v_cvt_pk_bf16_f32 v110, v184, v186
	v_cvt_pk_bf16_f32 v111, v188, v190
	s_waitcnt lgkmcnt(0)
	v_mfma_f32_32x32x16_bf16 v[80:95], v[96:99], v[140:143], v[64:79]
	ds_read_b128 v[96:99], v100 offset:57344
	v_add_u32_e32 v100, s14, v177
	s_waitcnt lgkmcnt(0)
	v_mfma_f32_32x32x16_bf16 v[64:79], v[96:99], v[140:143], v[64:79]
	ds_read_b128 v[96:99], v100 offset:49152
	s_waitcnt lgkmcnt(0)
	v_mfma_f32_32x32x16_bf16 v[80:95], v[96:99], v[136:139], v[80:95]
	ds_read_b128 v[96:99], v100 offset:57344
	v_add_u32_e32 v100, s14, v175
	s_waitcnt lgkmcnt(0)
	v_mfma_f32_32x32x16_bf16 v[64:79], v[96:99], v[136:139], v[64:79]
	ds_read_b128 v[96:99], v100 offset:49152
	s_waitcnt lgkmcnt(0)
	v_mfma_f32_32x32x16_bf16 v[80:95], v[96:99], v[132:135], v[80:95]
	ds_read_b128 v[96:99], v100 offset:57344
	v_add_u32_e32 v100, s14, v173
	s_waitcnt lgkmcnt(0)
	v_mfma_f32_32x32x16_bf16 v[64:79], v[96:99], v[132:135], v[64:79]
	ds_read_b128 v[96:99], v100 offset:49152
	s_waitcnt lgkmcnt(0)
	v_mfma_f32_32x32x16_bf16 v[80:95], v[96:99], v[128:131], v[80:95]
	ds_read_b128 v[96:99], v100 offset:57344
	v_add_u32_e32 v100, s14, v171
	s_waitcnt lgkmcnt(0)
	v_mfma_f32_32x32x16_bf16 v[64:79], v[96:99], v[128:131], v[64:79]
	ds_read_b128 v[96:99], v100 offset:49152
	s_waitcnt lgkmcnt(0)
	v_mfma_f32_32x32x16_bf16 v[80:95], v[96:99], v[124:127], v[80:95]
	ds_read_b128 v[96:99], v100 offset:57344
	v_add_u32_e32 v100, s14, v169
	s_waitcnt lgkmcnt(0)
	v_mfma_f32_32x32x16_bf16 v[64:79], v[96:99], v[124:127], v[64:79]
	ds_read_b128 v[96:99], v100 offset:49152
	s_waitcnt lgkmcnt(0)
	v_mfma_f32_32x32x16_bf16 v[80:95], v[96:99], v[120:123], v[80:95]
	ds_read_b128 v[96:99], v100 offset:57344
	v_add_u32_e32 v100, s14, v167
	s_waitcnt lgkmcnt(0)
	v_mfma_f32_32x32x16_bf16 v[64:79], v[96:99], v[120:123], v[64:79]
	ds_read_b128 v[96:99], v100 offset:49152
	s_waitcnt lgkmcnt(0)
	v_mfma_f32_32x32x16_bf16 v[80:95], v[96:99], v[116:119], v[80:95]
	ds_read_b128 v[96:99], v100 offset:57344
	ds_read_b128 v[100:103], v104 offset:49152
	ds_read_b128 v[104:107], v104 offset:57344
	s_waitcnt lgkmcnt(2)
	v_mfma_f32_32x32x16_bf16 v[64:79], v[96:99], v[116:119], v[64:79]
	v_cvt_pk_bf16_f32 v96, v206, v200
	v_cvt_pk_bf16_f32 v97, v202, v204
	v_cvt_pk_bf16_f32 v98, v216, v218
	v_cvt_pk_bf16_f32 v99, v220, v222
	v_cvt_pk_bf16_f32 v116, v198, v196
	v_cvt_pk_bf16_f32 v117, v192, v194
	v_cvt_pk_bf16_f32 v118, v208, v210
	s_waitcnt lgkmcnt(1)
	v_mfma_f32_32x32x16_bf16 v[80:95], v[100:103], v[112:115], v[80:95]
	v_cvt_pk_bf16_f32 v100, v168, v156
	v_cvt_pk_bf16_f32 v101, v158, v166
	v_cvt_pk_bf16_f32 v102, v176, v178
	v_cvt_pk_bf16_f32 v103, v180, v182
	v_cvt_pk_bf16_f32 v119, v212, v214
	s_waitcnt lgkmcnt(0)
	v_mfma_f32_32x32x16_bf16 v[64:79], v[104:107], v[112:115], v[64:79]
	v_add_u32_e32 v147, s49, v147
	ds_read_b64_tr_b16 v[104:105], v147 offset:0
	ds_read_b64_tr_b16 v[106:107], v147 offset:0x100
	ds_read_b64_tr_b16 v[112:113], v147 offset:0x1000
	ds_read_b64_tr_b16 v[114:115], v147 offset:0x1100
	ds_read_b64_tr_b16 v[120:121], v147 offset:0x2000
	ds_read_b64_tr_b16 v[122:123], v147 offset:0x2100
	ds_read_b64_tr_b16 v[124:125], v147 offset:0x3000
	ds_read_b64_tr_b16 v[126:127], v147 offset:0x3100
	ds_read_b64_tr_b16 v[128:129], v147 offset:0x200
	ds_read_b64_tr_b16 v[130:131], v147 offset:0x300
	ds_read_b64_tr_b16 v[132:133], v147 offset:0x1200
	ds_read_b64_tr_b16 v[134:135], v147 offset:0x1300
	ds_read_b64_tr_b16 v[136:137], v147 offset:0x2200
	ds_read_b64_tr_b16 v[138:139], v147 offset:0x2300
	ds_read_b64_tr_b16 v[140:141], v147 offset:0x3200
	ds_read_b64_tr_b16 v[142:143], v147 offset:0x3300
	s_waitcnt lgkmcnt(8)
	s_nop 0
	v_mfma_f32_32x32x16_bf16 v[48:63], v[104:107], v[108:111], v[48:63]
	s_nop 1
	v_exp_f32_e32 v171, v80
	v_exp_f32_e32 v173, v81
	v_exp_f32_e32 v175, v82
	v_exp_f32_e32 v185, v83
	s_nop 2
	v_exp_f32_e32 v157, v64
	v_exp_f32_e32 v159, v65
	v_exp_f32_e32 v167, v66
	v_mfma_f32_32x32x16_bf16 v[48:63], v[112:115], v[96:99], v[48:63]
	v_exp_f32_e32 v177, v67
	v_mfma_f32_32x32x16_bf16 v[48:63], v[120:123], v[100:103], v[48:63]
	v_mfma_f32_32x32x16_bf16 v[48:63], v[124:127], v[116:119], v[48:63]
	ds_read_b64_tr_b16 v[64:65], v147 offset:0x400
	ds_read_b64_tr_b16 v[66:67], v147 offset:0x500
	ds_read_b64_tr_b16 v[80:81], v147 offset:0x1400
	ds_read_b64_tr_b16 v[82:83], v147 offset:0x1500
	ds_read_b64_tr_b16 v[104:105], v147 offset:0x2400
	ds_read_b64_tr_b16 v[106:107], v147 offset:0x2500
	ds_read_b64_tr_b16 v[112:113], v147 offset:0x3400
	ds_read_b64_tr_b16 v[114:115], v147 offset:0x3500
	s_waitcnt lgkmcnt(8)
	v_mfma_f32_32x32x16_bf16 v[32:47], v[128:131], v[108:111], v[32:47]
	v_exp_f32_e32 v187, v84
	v_exp_f32_e32 v189, v85
	v_exp_f32_e32 v191, v86
	v_exp_f32_e32 v207, v87
	v_exp_f32_e32 v179, v68
	v_exp_f32_e32 v181, v69
	v_exp_f32_e32 v183, v70
	v_mfma_f32_32x32x16_bf16 v[32:47], v[132:135], v[96:99], v[32:47]
	v_exp_f32_e32 v199, v71
	v_mfma_f32_32x32x16_bf16 v[32:47], v[136:139], v[100:103], v[32:47]
	v_mfma_f32_32x32x16_bf16 v[32:47], v[140:143], v[116:119], v[32:47]
	ds_read_b64_tr_b16 v[68:69], v147 offset:0x600
	ds_read_b64_tr_b16 v[70:71], v147 offset:0x700
	ds_read_b64_tr_b16 v[84:85], v147 offset:0x1600
	ds_read_b64_tr_b16 v[86:87], v147 offset:0x1700
	ds_read_b64_tr_b16 v[120:121], v147 offset:0x2600
	ds_read_b64_tr_b16 v[122:123], v147 offset:0x2700
	ds_read_b64_tr_b16 v[124:125], v147 offset:0x3600
	ds_read_b64_tr_b16 v[126:127], v147 offset:0x3700
	s_waitcnt lgkmcnt(8)
; #define SBAR() __builtin_amdgcn_sched_barrier(0)
; __device__ __forceinline__ void attn_dense_body(const bf16* Qb, const bf16* __restrict__ Kh, const bf16* __restrict__ Vh, const bf16* __restrict__ Zb, ...
;     ...
;   pv_d03(o, vb0 + sP * (int)SHM_V, pa0, pa1, pa2, pa3, pB0, pB1);
;   finishSM4<16>(pB0, pB1, l_reg, pa0, pa1, pa2, pa3); SBAR();
;   pv_d02(o, vb0 + sC * (int)SHM_V, pa0, pa1, pa2, pa3);
;     ...
;   { int lb = (wid * QBLK + r32) * LDO + 4 * hi; asm volatile("" : "+v"(lb));
;     unsigned short* Ow = (unsigned short*)Ob + lb; const unsigned short* Zw = (const unsigned short*)Zb + lb;
; #pragma unroll
;     for (int d0 = 0; d0 < 4; ++d0)
; #pragma unroll
;       for (int g = 0; g < 4; ++g) { const int co = d0 * 32 + 8 * g; const unsigned long long zz = *(const unsigned long long*)(Zw + co);
	v_mfma_f32_32x32x16_bf16 v[16:31], v[64:67], v[108:111], v[16:31]
	v_exp_f32_e32 v201, v88
	v_exp_f32_e32 v203, v89
	v_exp_f32_e32 v205, v90
	v_exp_f32_e32 v217, v91
	v_exp_f32_e32 v197, v72
	v_exp_f32_e32 v193, v73
	v_exp_f32_e32 v195, v74
	v_mfma_f32_32x32x16_bf16 v[16:31], v[80:83], v[96:99], v[16:31]
	v_exp_f32_e32 v209, v75
	v_mfma_f32_32x32x16_bf16 v[16:31], v[104:107], v[100:103], v[16:31]
	v_mfma_f32_32x32x16_bf16 v[16:31], v[112:115], v[116:119], v[16:31]
	s_waitcnt lgkmcnt(0)
	v_mov_b32_e32 v149, v161
	v_add_f32_e64 v64, v170, v148
	v_add_f32_e64 v65, v171, v149
	v_mfma_f32_32x32x16_bf16 v[0:15], v[68:71], v[108:111], v[0:15]
	v_add_f32_e64 v64, v172, v64
	v_add_f32_e64 v65, v173, v65
	v_exp_f32_e32 v219, v92
	v_pk_add_f32 v[64:65], v[174:175], v[64:65]
	v_exp_f32_e32 v221, v93
	v_pk_add_f32 v[64:65], v[184:185], v[64:65]
	v_exp_f32_e32 v223, v94
	v_pk_add_f32 v[64:65], v[186:187], v[64:65]
	v_exp_f32_e32 v169, v95
	v_pk_add_f32 v[64:65], v[188:189], v[64:65]
	v_mfma_f32_32x32x16_bf16 v[0:15], v[84:87], v[96:99], v[0:15]
	v_add_f32_e64 v64, v190, v64
	v_add_f32_e64 v65, v191, v65
	v_exp_f32_e32 v211, v76
	v_pk_add_f32 v[64:65], v[206:207], v[64:65]
	v_exp_f32_e32 v213, v77
	v_pk_add_f32 v[64:65], v[200:201], v[64:65]
	v_exp_f32_e32 v215, v78
	v_pk_add_f32 v[64:65], v[202:203], v[64:65]
	v_mfma_f32_32x32x16_bf16 v[0:15], v[120:123], v[100:103], v[0:15]
	v_add_f32_e64 v64, v204, v64
	v_add_f32_e64 v65, v205, v65
	v_exp_f32_e32 v147, v79
	v_pk_add_f32 v[64:65], v[216:217], v[64:65]
	v_cvt_pk_bf16_f32 v66, v187, v189
	v_pk_add_f32 v[64:65], v[218:219], v[64:65]
	v_cvt_pk_bf16_f32 v67, v191, v207
	v_pk_add_f32 v[64:65], v[220:221], v[64:65]
	v_mfma_f32_32x32x16_bf16 v[0:15], v[124:127], v[116:119], v[0:15]
	v_add_f32_e64 v64, v222, v64
	v_add_f32_e64 v65, v223, v65
	v_cvt_pk_bf16_f32 v68, v201, v203
	v_add_f32_e64 v64, v168, v64
	v_add_f32_e64 v65, v169, v65
	v_cvt_pk_bf16_f32 v69, v205, v217
	v_pk_add_f32 v[64:65], v[156:157], v[64:65]
	v_cvt_pk_bf16_f32 v70, v219, v221
	v_pk_add_f32 v[64:65], v[158:159], v[64:65]
	v_cvt_pk_bf16_f32 v71, v223, v169
	v_pk_add_f32 v[64:65], v[166:167], v[64:65]
	v_cvt_pk_bf16_f32 v72, v157, v159
	v_pk_add_f32 v[64:65], v[176:177], v[64:65]
	v_cvt_pk_bf16_f32 v73, v167, v177
	v_pk_add_f32 v[64:65], v[178:179], v[64:65]
	v_cvt_pk_bf16_f32 v74, v179, v181
	v_pk_add_f32 v[64:65], v[180:181], v[64:65]
	v_cvt_pk_bf16_f32 v75, v183, v199
	v_pk_add_f32 v[64:65], v[182:183], v[64:65]
	v_cvt_pk_bf16_f32 v76, v197, v193
	v_pk_add_f32 v[64:65], v[198:199], v[64:65]
	v_cvt_pk_bf16_f32 v77, v195, v209
	v_pk_add_f32 v[64:65], v[196:197], v[64:65]
	v_cvt_pk_bf16_f32 v78, v211, v213
	v_pk_add_f32 v[64:65], v[192:193], v[64:65]
	v_cvt_pk_bf16_f32 v79, v215, v147
	v_pk_add_f32 v[64:65], v[194:195], v[64:65]
	s_nop 0
	v_pk_add_f32 v[64:65], v[208:209], v[64:65]
	s_nop 0
	v_pk_add_f32 v[64:65], v[210:211], v[64:65]
	s_nop 0
	v_pk_add_f32 v[64:65], v[212:213], v[64:65]
	s_nop 0
	v_pk_add_f32 v[64:65], v[214:215], v[64:65]
	s_nop 0
	v_pk_add_f32 v[64:65], v[146:147], v[64:65]
	s_nop 0
	v_pk_add_f32 v[112:113], v[64:65], v[64:65] op_sel:[0,1] op_sel_hi:[1,0]
	v_cvt_pk_bf16_f32 v64, v171, v173
	v_cvt_pk_bf16_f32 v65, v175, v185
	v_lshlrev_b32_e32 v222, 2, v245
	v_lshl_add_u32 v222, v160, 10, v222
	v_ashrrev_i32_e32 v223, 31, v222
	v_lshlrev_b64 v[222:223], 1, v[222:223]
	v_lshl_add_u64 v[220:221], s[40:41], 0, v[222:223]
	global_load_dwordx2 v[162:163], v[220:221], off
	global_load_dwordx2 v[164:165], v[220:221], off offset:16
	global_load_dwordx2 v[166:167], v[220:221], off offset:32
	global_load_dwordx2 v[168:169], v[220:221], off offset:48
	global_load_dwordx2 v[170:171], v[220:221], off offset:64
	global_load_dwordx2 v[172:173], v[220:221], off offset:80
	global_load_dwordx2 v[174:175], v[220:221], off offset:96
	global_load_dwordx2 v[176:177], v[220:221], off offset:112
	global_load_dwordx2 v[178:179], v[220:221], off offset:128
	global_load_dwordx2 v[180:181], v[220:221], off offset:144
	global_load_dwordx2 v[182:183], v[220:221], off offset:160
	global_load_dwordx2 v[184:185], v[220:221], off offset:176
	global_load_dwordx2 v[186:187], v[220:221], off offset:192
	global_load_dwordx2 v[188:189], v[220:221], off offset:208
	global_load_dwordx2 v[190:191], v[220:221], off offset:224
	global_load_dwordx2 v[192:193], v[220:221], off offset:240
	ds_read_b64_tr_b16 v[80:81], v246 offset:0
	ds_read_b64_tr_b16 v[82:83], v246 offset:0x100
	ds_read_b64_tr_b16 v[84:85], v246 offset:0x1000
	ds_read_b64_tr_b16 v[86:87], v246 offset:0x1100
	ds_read_b64_tr_b16 v[88:89], v246 offset:0x2000
	ds_read_b64_tr_b16 v[90:91], v246 offset:0x2100
	ds_read_b64_tr_b16 v[92:93], v246 offset:0x3000
	ds_read_b64_tr_b16 v[94:95], v246 offset:0x3100
	ds_read_b64_tr_b16 v[96:97], v246 offset:0x200
	ds_read_b64_tr_b16 v[98:99], v246 offset:0x300
	ds_read_b64_tr_b16 v[100:101], v246 offset:0x1200
	ds_read_b64_tr_b16 v[102:103], v246 offset:0x1300
	ds_read_b64_tr_b16 v[104:105], v246 offset:0x2200
	ds_read_b64_tr_b16 v[106:107], v246 offset:0x2300
	ds_read_b64_tr_b16 v[108:109], v246 offset:0x3200
	ds_read_b64_tr_b16 v[110:111], v246 offset:0x3300
	s_waitcnt lgkmcnt(8)
	s_nop 1
	v_mfma_f32_32x32x16_bf16 v[48:63], v[80:83], v[64:67], v[48:63]
	v_mfma_f32_32x32x16_bf16 v[48:63], v[84:87], v[68:71], v[48:63]
	v_mfma_f32_32x32x16_bf16 v[48:63], v[88:91], v[72:75], v[48:63]
	v_mfma_f32_32x32x16_bf16 v[48:63], v[92:95], v[76:79], v[48:63]
	ds_read_b64_tr_b16 v[80:81], v246 offset:0x400
	ds_read_b64_tr_b16 v[82:83], v246 offset:0x500
	ds_read_b64_tr_b16 v[84:85], v246 offset:0x1400
	ds_read_b64_tr_b16 v[86:87], v246 offset:0x1500
	ds_read_b64_tr_b16 v[88:89], v246 offset:0x2400
	ds_read_b64_tr_b16 v[90:91], v246 offset:0x2500
	ds_read_b64_tr_b16 v[92:93], v246 offset:0x3400
	ds_read_b64_tr_b16 v[94:95], v246 offset:0x3500
	s_waitcnt lgkmcnt(8)
; #define SBAR() __builtin_amdgcn_sched_barrier(0)
; __device__ __forceinline__ unsigned cvtpk(float lo, float hi) { return pg8::cvt_pk_bf16(lo, hi); }
; #define PV_RD2(D0, X) const s16x4 X##l0 = tr_read<v_rd_off2(D0, 0, 0)>(vb), X##h0 = tr_read<v_rd_off2(D0, 0, 1)>(vb), X##l1 = tr_read<v_rd_off2(D0, 1, 0)>(vb), X##h1 = tr_read<v_rd_off2(D0, 1, 1)>(vb), \
;                               X##l2 = tr_read<v_rd_off2(D0, 2, 0)>(vb), X##h2 = tr_read<v_rd_off2(D0, 2, 1)>(vb), X##l3 = tr_read<v_rd_off2(D0, 3, 0)>(vb), X##h3 = tr_read<v_rd_off2(D0, 3, 1)>(vb)
; __device__ __forceinline__ void pv_d02(f32x16* o, int vb, bf16x8 pa0, bf16x8 pa1, bf16x8 pa2, bf16x8 pa3) {
;   PV_RD2(0, a);
;   PV_RD2(1, b); asm volatile("s_waitcnt lgkmcnt(8)" ::: "memory"); SBAR(); PV_MM2(o[0], a); SBAR();
;   PV_RD2(2, c); asm volatile("s_waitcnt lgkmcnt(8)" ::: "memory"); SBAR(); PV_MM2(o[1], b); SBAR();
;   PV_RD2(3, d); asm volatile("s_waitcnt lgkmcnt(8)" ::: "memory"); SBAR(); PV_MM2(o[2], c); SBAR();
;   asm volatile("s_waitcnt lgkmcnt(0)" ::: "memory"); SBAR(); PV_MM2(o[3], d);
; }
; __device__ __forceinline__ void attn_dense_body(const bf16* Qb, const bf16* __restrict__ Kh, const bf16* __restrict__ Vh, const bf16* __restrict__ Zb, ...
;     ...
;   { auto rr = __builtin_amdgcn_permlane32_swap(__float_as_uint(l_reg), __float_as_uint(l_reg), false, false); l_reg = __uint_as_float(rr[0]) + __uint_as_float(rr[1]); }
;   const float rl = __builtin_amdgcn_rcpf(l_reg);
;   { int lb = (wid * QBLK + r32) * LDO + 4 * hi; asm volatile("" : "+v"(lb));
;     unsigned short* Ow = (unsigned short*)Ob + lb; const unsigned short* Zw = (const unsigned short*)Zb + lb;
; #pragma unroll
;     for (int d0 = 0; d0 < 4; ++d0)
; #pragma unroll
;       for (int g = 0; g < 4; ++g) { const int co = d0 * 32 + 8 * g; const unsigned long long zz = *(const unsigned long long*)(Zw + co);
;         const float z0 = __uint_as_float((unsigned)(zz << 16)), z1 = __uint_as_float((unsigned)zz & 0xffff0000u), z2 = __uint_as_float((unsigned)(zz >> 32) << 16), z3 = __uint_as_float((unsigned)(zz >> 32) & 0xffff0000u);
;         const unsigned w0 = cvtpk(o[d0][4 * g + 0] * rl * z0, o[d0][4 * g + 1] * rl * z1), w1 = cvtpk(o[d0][4 * g + 2] * rl * z2, o[d0][4 * g + 3] * rl * z3);
	v_mfma_f32_32x32x16_bf16 v[32:47], v[96:99], v[64:67], v[32:47]
	v_mfma_f32_32x32x16_bf16 v[32:47], v[100:103], v[68:71], v[32:47]
	v_mfma_f32_32x32x16_bf16 v[32:47], v[104:107], v[72:75], v[32:47]
	v_mfma_f32_32x32x16_bf16 v[32:47], v[108:111], v[76:79], v[32:47]
	ds_read_b64_tr_b16 v[96:97], v246 offset:0x600
	ds_read_b64_tr_b16 v[98:99], v246 offset:0x700
	ds_read_b64_tr_b16 v[100:101], v246 offset:0x1600
	ds_read_b64_tr_b16 v[102:103], v246 offset:0x1700
	ds_read_b64_tr_b16 v[104:105], v246 offset:0x2600
	ds_read_b64_tr_b16 v[106:107], v246 offset:0x2700
	ds_read_b64_tr_b16 v[108:109], v246 offset:0x3600
	ds_read_b64_tr_b16 v[110:111], v246 offset:0x3700
	s_waitcnt lgkmcnt(8)
	v_mfma_f32_32x32x16_bf16 v[16:31], v[80:83], v[64:67], v[16:31]
	v_mfma_f32_32x32x16_bf16 v[16:31], v[84:87], v[68:71], v[16:31]
	v_mfma_f32_32x32x16_bf16 v[16:31], v[88:91], v[72:75], v[16:31]
	v_mfma_f32_32x32x16_bf16 v[16:31], v[92:95], v[76:79], v[16:31]
	s_waitcnt lgkmcnt(0)
	v_mfma_f32_32x32x16_bf16 v[0:15], v[96:99], v[64:67], v[0:15]
	v_mov_b32_e32 v64, v112
	s_nop 1
	v_permlane32_swap_b32_e32 v112, v64
	v_add_f32_e32 v64, v112, v64
	s_add_i32 s51, s51, s62
	s_cmp_ge_i32 s51, s6
	v_mfma_f32_32x32x16_bf16 v[0:15], v[100:103], v[68:71], v[0:15]
	v_rcp_f32_e32 v68, v64
	v_lshlrev_b32_e32 v64, 2, v245
	v_lshl_add_u32 v64, v160, 10, v64
	v_ashrrev_i32_e32 v65, 31, v64
	v_lshlrev_b64 v[66:67], 1, v[64:65]
	v_lshl_add_u64 v[64:65], s[24:25], 0, v[66:67]
	v_mfma_f32_32x32x16_bf16 v[0:15], v[104:107], v[72:75], v[0:15]
	v_mfma_f32_32x32x16_bf16 v[0:15], v[108:111], v[76:79], v[0:15]
	v_mul_f32_e32 v48, v48, v68
	v_mul_f32_e32 v49, v49, v68
	v_mul_f32_e32 v50, v50, v68
	v_mul_f32_e32 v51, v51, v68
	v_mul_f32_e32 v52, v52, v68
	v_mul_f32_e32 v53, v53, v68
	v_mul_f32_e32 v54, v54, v68
	v_mul_f32_e32 v55, v55, v68
	v_mul_f32_e32 v56, v56, v68
	v_mul_f32_e32 v57, v57, v68
	v_mul_f32_e32 v58, v58, v68
	v_mul_f32_e32 v59, v59, v68
	v_mul_f32_e32 v60, v60, v68
	v_mul_f32_e32 v61, v61, v68
	v_mul_f32_e32 v62, v62, v68
	v_mul_f32_e32 v63, v63, v68
	v_mul_f32_e32 v32, v32, v68
	v_mul_f32_e32 v33, v33, v68
	v_mul_f32_e32 v34, v34, v68
	v_mul_f32_e32 v35, v35, v68
	v_mul_f32_e32 v36, v36, v68
	v_mul_f32_e32 v37, v37, v68
	v_mul_f32_e32 v38, v38, v68
	v_mul_f32_e32 v39, v39, v68
	v_mul_f32_e32 v40, v40, v68
	v_mul_f32_e32 v41, v41, v68
	v_mul_f32_e32 v42, v42, v68
	v_mul_f32_e32 v43, v43, v68
	v_mul_f32_e32 v44, v44, v68
	v_mul_f32_e32 v45, v45, v68
	v_mul_f32_e32 v46, v46, v68
	v_mul_f32_e32 v47, v47, v68
	v_mul_f32_e32 v16, v16, v68
	v_mul_f32_e32 v17, v17, v68
	v_mul_f32_e32 v18, v18, v68
	v_mul_f32_e32 v19, v19, v68
	v_mul_f32_e32 v20, v20, v68
	v_mul_f32_e32 v21, v21, v68
	v_mul_f32_e32 v22, v22, v68
	v_mul_f32_e32 v23, v23, v68
	v_mul_f32_e32 v24, v24, v68
	v_mul_f32_e32 v25, v25, v68
	v_mul_f32_e32 v26, v26, v68
	v_mul_f32_e32 v27, v27, v68
	v_mul_f32_e32 v28, v28, v68
	v_mul_f32_e32 v29, v29, v68
	v_mul_f32_e32 v30, v30, v68
	v_mul_f32_e32 v31, v31, v68
	v_mul_f32_e32 v0, v0, v68
	v_mul_f32_e32 v1, v1, v68
	v_mul_f32_e32 v2, v2, v68
	v_mul_f32_e32 v3, v3, v68
	v_mul_f32_e32 v4, v4, v68
	v_mul_f32_e32 v5, v5, v68
	v_mul_f32_e32 v6, v6, v68
	v_mul_f32_e32 v7, v7, v68
	v_mul_f32_e32 v8, v8, v68
	v_mul_f32_e32 v9, v9, v68
	v_mul_f32_e32 v10, v10, v68
	v_mul_f32_e32 v11, v11, v68
	v_mul_f32_e32 v12, v12, v68
	v_mul_f32_e32 v13, v13, v68
	v_mul_f32_e32 v14, v14, v68
	v_mul_f32_e32 v15, v15, v68
	s_waitcnt vmcnt(0)
; __device__ __forceinline__ unsigned cvtpk(float lo, float hi) { return pg8::cvt_pk_bf16(lo, hi); }
; __device__ __forceinline__ void attn_dense_body(const bf16* Qb, const bf16* __restrict__ Kh, const bf16* __restrict__ Vh, const bf16* __restrict__ Zb, ...
;     ...
;   { int lb = (wid * QBLK + r32) * LDO + 4 * hi; asm volatile("" : "+v"(lb));
;     unsigned short* Ow = (unsigned short*)Ob + lb; const unsigned short* Zw = (const unsigned short*)Zb + lb;
; #pragma unroll
;     for (int d0 = 0; d0 < 4; ++d0)
; #pragma unroll
;       for (int g = 0; g < 4; ++g) { const int co = d0 * 32 + 8 * g; const unsigned long long zz = *(const unsigned long long*)(Zw + co);
;         const float z0 = __uint_as_float((unsigned)(zz << 16)), z1 = __uint_as_float((unsigned)zz & 0xffff0000u), z2 = __uint_as_float((unsigned)(zz >> 32) << 16), z3 = __uint_as_float((unsigned)(zz >> 32) & 0xffff0000u);
;         const unsigned w0 = cvtpk(o[d0][4 * g + 0] * rl * z0, o[d0][4 * g + 1] * rl * z1), w1 = cvtpk(o[d0][4 * g + 2] * rl * z2, o[d0][4 * g + 3] * rl * z3);
;         *(unsigned long long*)(Ow + co) = (unsigned long long)w0 | ((unsigned long long)w1 << 32); } }
	v_lshlrev_b32_e32 v194, 16, v162
	v_and_b32_e32 v195, 0xffff0000, v162
	v_lshlrev_b32_e32 v196, 16, v163
	v_and_b32_e32 v197, 0xffff0000, v163
	v_mul_f32_e32 v48, v48, v194
	v_mul_f32_e32 v49, v49, v195
	v_mul_f32_e32 v50, v50, v196
	v_mul_f32_e32 v51, v51, v197
	v_cvt_pk_bf16_f32 v48, v48, v49
	v_cvt_pk_bf16_f32 v49, v50, v51
	global_store_dwordx2 v[64:65], v[48:49], off
	v_lshlrev_b32_e32 v194, 16, v164
	v_and_b32_e32 v195, 0xffff0000, v164
	v_lshlrev_b32_e32 v196, 16, v165
	v_and_b32_e32 v197, 0xffff0000, v165
	v_mul_f32_e32 v52, v52, v194
	v_mul_f32_e32 v53, v53, v195
	v_mul_f32_e32 v54, v54, v196
	v_mul_f32_e32 v55, v55, v197
	v_cvt_pk_bf16_f32 v52, v52, v53
	v_cvt_pk_bf16_f32 v53, v54, v55
	global_store_dwordx2 v[64:65], v[52:53], off offset:16
	v_lshlrev_b32_e32 v194, 16, v166
	v_and_b32_e32 v195, 0xffff0000, v166
	v_lshlrev_b32_e32 v196, 16, v167
	v_and_b32_e32 v197, 0xffff0000, v167
	v_mul_f32_e32 v56, v56, v194
	v_mul_f32_e32 v57, v57, v195
	v_mul_f32_e32 v58, v58, v196
	v_mul_f32_e32 v59, v59, v197
	v_cvt_pk_bf16_f32 v56, v56, v57
	v_cvt_pk_bf16_f32 v57, v58, v59
	global_store_dwordx2 v[64:65], v[56:57], off offset:32
	v_lshlrev_b32_e32 v194, 16, v168
	v_and_b32_e32 v195, 0xffff0000, v168
	v_lshlrev_b32_e32 v196, 16, v169
	v_and_b32_e32 v197, 0xffff0000, v169
	v_mul_f32_e32 v60, v60, v194
	v_mul_f32_e32 v61, v61, v195
	v_mul_f32_e32 v62, v62, v196
	v_mul_f32_e32 v63, v63, v197
	v_cvt_pk_bf16_f32 v60, v60, v61
	v_cvt_pk_bf16_f32 v61, v62, v63
	global_store_dwordx2 v[64:65], v[60:61], off offset:48
	v_lshlrev_b32_e32 v194, 16, v170
	v_and_b32_e32 v195, 0xffff0000, v170
	v_lshlrev_b32_e32 v196, 16, v171
	v_and_b32_e32 v197, 0xffff0000, v171
	v_mul_f32_e32 v32, v32, v194
	v_mul_f32_e32 v33, v33, v195
	v_mul_f32_e32 v34, v34, v196
	v_mul_f32_e32 v35, v35, v197
	v_cvt_pk_bf16_f32 v32, v32, v33
	v_cvt_pk_bf16_f32 v33, v34, v35
	global_store_dwordx2 v[64:65], v[32:33], off offset:64
	v_lshlrev_b32_e32 v194, 16, v172
	v_and_b32_e32 v195, 0xffff0000, v172
	v_lshlrev_b32_e32 v196, 16, v173
	v_and_b32_e32 v197, 0xffff0000, v173
	v_mul_f32_e32 v36, v36, v194
	v_mul_f32_e32 v37, v37, v195
	v_mul_f32_e32 v38, v38, v196
	v_mul_f32_e32 v39, v39, v197
	v_cvt_pk_bf16_f32 v36, v36, v37
	v_cvt_pk_bf16_f32 v37, v38, v39
	global_store_dwordx2 v[64:65], v[36:37], off offset:80
	v_lshlrev_b32_e32 v194, 16, v174
	v_and_b32_e32 v195, 0xffff0000, v174
	v_lshlrev_b32_e32 v196, 16, v175
	v_and_b32_e32 v197, 0xffff0000, v175
	v_mul_f32_e32 v40, v40, v194
	v_mul_f32_e32 v41, v41, v195
	v_mul_f32_e32 v42, v42, v196
	v_mul_f32_e32 v43, v43, v197
	v_cvt_pk_bf16_f32 v40, v40, v41
	v_cvt_pk_bf16_f32 v41, v42, v43
	global_store_dwordx2 v[64:65], v[40:41], off offset:96
	v_lshlrev_b32_e32 v194, 16, v176
	v_and_b32_e32 v195, 0xffff0000, v176
	v_lshlrev_b32_e32 v196, 16, v177
	v_and_b32_e32 v197, 0xffff0000, v177
	v_mul_f32_e32 v44, v44, v194
	v_mul_f32_e32 v45, v45, v195
	v_mul_f32_e32 v46, v46, v196
	v_mul_f32_e32 v47, v47, v197
	v_cvt_pk_bf16_f32 v44, v44, v45
	v_cvt_pk_bf16_f32 v45, v46, v47
	global_store_dwordx2 v[64:65], v[44:45], off offset:112
	v_lshlrev_b32_e32 v194, 16, v178
	v_and_b32_e32 v195, 0xffff0000, v178
	v_lshlrev_b32_e32 v196, 16, v179
	v_and_b32_e32 v197, 0xffff0000, v179
	v_mul_f32_e32 v16, v16, v194
	v_mul_f32_e32 v17, v17, v195
	v_mul_f32_e32 v18, v18, v196
	v_mul_f32_e32 v19, v19, v197
	v_cvt_pk_bf16_f32 v16, v16, v17
	v_cvt_pk_bf16_f32 v17, v18, v19
	global_store_dwordx2 v[64:65], v[16:17], off offset:128
	v_lshlrev_b32_e32 v194, 16, v180
	v_and_b32_e32 v195, 0xffff0000, v180
	v_lshlrev_b32_e32 v196, 16, v181
	v_and_b32_e32 v197, 0xffff0000, v181
	v_mul_f32_e32 v20, v20, v194
	v_mul_f32_e32 v21, v21, v195
	v_mul_f32_e32 v22, v22, v196
	v_mul_f32_e32 v23, v23, v197
	v_cvt_pk_bf16_f32 v20, v20, v21
	v_cvt_pk_bf16_f32 v21, v22, v23
	global_store_dwordx2 v[64:65], v[20:21], off offset:144
	v_lshlrev_b32_e32 v194, 16, v182
	v_and_b32_e32 v195, 0xffff0000, v182
	v_lshlrev_b32_e32 v196, 16, v183
	v_and_b32_e32 v197, 0xffff0000, v183
	v_mul_f32_e32 v24, v24, v194
	v_mul_f32_e32 v25, v25, v195
	v_mul_f32_e32 v26, v26, v196
	v_mul_f32_e32 v27, v27, v197
	v_cvt_pk_bf16_f32 v24, v24, v25
	v_cvt_pk_bf16_f32 v25, v26, v27
	global_store_dwordx2 v[64:65], v[24:25], off offset:160
	v_lshlrev_b32_e32 v194, 16, v184
	v_and_b32_e32 v195, 0xffff0000, v184
	v_lshlrev_b32_e32 v196, 16, v185
	v_and_b32_e32 v197, 0xffff0000, v185
	v_mul_f32_e32 v28, v28, v194
	v_mul_f32_e32 v29, v29, v195
	v_mul_f32_e32 v30, v30, v196
	v_mul_f32_e32 v31, v31, v197
	v_cvt_pk_bf16_f32 v28, v28, v29
	v_cvt_pk_bf16_f32 v29, v30, v31
	global_store_dwordx2 v[64:65], v[28:29], off offset:176
	v_lshlrev_b32_e32 v194, 16, v186
	v_and_b32_e32 v195, 0xffff0000, v186
	v_lshlrev_b32_e32 v196, 16, v187
	v_and_b32_e32 v197, 0xffff0000, v187
	v_mul_f32_e32 v0, v0, v194
	v_mul_f32_e32 v1, v1, v195
	v_mul_f32_e32 v2, v2, v196
	v_mul_f32_e32 v3, v3, v197
	v_cvt_pk_bf16_f32 v0, v0, v1
	v_cvt_pk_bf16_f32 v1, v2, v3
	global_store_dwordx2 v[64:65], v[0:1], off offset:192
	v_lshlrev_b32_e32 v194, 16, v188
	v_and_b32_e32 v195, 0xffff0000, v188
	v_lshlrev_b32_e32 v196, 16, v189
	v_and_b32_e32 v197, 0xffff0000, v189
	v_mul_f32_e32 v4, v4, v194
	v_mul_f32_e32 v5, v5, v195
	v_mul_f32_e32 v6, v6, v196
	v_mul_f32_e32 v7, v7, v197
	v_cvt_pk_bf16_f32 v4, v4, v5
	v_cvt_pk_bf16_f32 v5, v6, v7
	global_store_dwordx2 v[64:65], v[4:5], off offset:208
	v_lshlrev_b32_e32 v194, 16, v190
	v_and_b32_e32 v195, 0xffff0000, v190
	v_lshlrev_b32_e32 v196, 16, v191
	v_and_b32_e32 v197, 0xffff0000, v191
	v_mul_f32_e32 v8, v8, v194
	v_mul_f32_e32 v9, v9, v195
	v_mul_f32_e32 v10, v10, v196
	v_mul_f32_e32 v11, v11, v197
	v_cvt_pk_bf16_f32 v8, v8, v9
	v_cvt_pk_bf16_f32 v9, v10, v11
	global_store_dwordx2 v[64:65], v[8:9], off offset:224
	v_lshlrev_b32_e32 v194, 16, v192
	v_and_b32_e32 v195, 0xffff0000, v192
	v_lshlrev_b32_e32 v196, 16, v193
	v_and_b32_e32 v197, 0xffff0000, v193
	v_mul_f32_e32 v12, v12, v194
	v_mul_f32_e32 v13, v13, v195
	v_mul_f32_e32 v14, v14, v196
	v_mul_f32_e32 v15, v15, v197
	v_cvt_pk_bf16_f32 v12, v12, v13
	v_cvt_pk_bf16_f32 v13, v14, v15
	global_store_dwordx2 v[64:65], v[12:13], off offset:240
	s_cbranch_scc0 .LBB0_112
